# as previous but post-MMA barrier 8 MFMAs early
# speedup vs baseline: 1.0081x; 1.0081x over previous
.LBB0_143:
	s_add_u32 s26, s16, 0xfffc0080
	s_addc_u32 s27, s17, -1
	s_add_i32 s34, 0, 0x10000
	s_cmp_eq_u32 s37, 12
	s_cselect_b32 s31, s9, s27
	s_cselect_b32 s30, s25, s26
	v_add_u32_e32 v138, s34, v141
	s_cselect_b32 s27, s7, s36
	s_cselect_b32 s26, s28, s29
	s_add_i32 s40, 0, 0x14000
	ds_read_b128 v[144:147], v138
	ds_read_b128 v[148:151], v138 offset:1024
	ds_read_b128 v[152:155], v138 offset:2048
	ds_read_b128 v[156:159], v138 offset:3072
	v_add_u32_e32 v138, s40, v141
	ds_read_b128 v[160:163], v138
	ds_read_b128 v[164:167], v138 offset:1024
	ds_read_b128 v[168:171], v138 offset:2048
	ds_read_b128 v[172:175], v138 offset:3072
	v_lshl_add_u64 v[138:139], s[16:17], 0, v[132:133]
	s_add_i32 m0, s53, 0xc000
	ds_read_b128 v[176:179], v143
	ds_read_b128 v[180:183], v143 offset:1024
	ds_read_b128 v[184:187], v143 offset:2048
	ds_read_b128 v[188:191], v143 offset:3072
	ds_read_b128 v[192:195], v143 offset:4096
	ds_read_b128 v[196:199], v143 offset:5120
	ds_read_b128 v[200:203], v143 offset:6144
	ds_read_b128 v[204:207], v143 offset:7168
	global_load_lds_dwordx4 v[138:139], off
	v_lshl_add_u64 v[138:139], s[16:17], 0, v[134:135]
	s_add_i32 m0, s53, 0xe000
	s_nop 0
	global_load_lds_dwordx4 v[138:139], off
	s_waitcnt vmcnt(8)
	s_waitcnt lgkmcnt(0)
	s_barrier
	s_setprio 1
	s_waitcnt lgkmcnt(0)
	v_mfma_f32_16x16x32_bf16 v[126:129], v[144:147], v[176:179], v[126:129]
	v_mfma_f32_16x16x32_bf16 v[126:129], v[148:151], v[180:183], v[126:129]
	v_mfma_f32_16x16x32_bf16 v[118:121], v[152:155], v[176:179], v[118:121]
	v_mfma_f32_16x16x32_bf16 v[118:121], v[156:159], v[180:183], v[118:121]
	v_mfma_f32_16x16x32_bf16 v[110:113], v[144:147], v[184:187], v[110:113]
	v_mfma_f32_16x16x32_bf16 v[110:113], v[148:151], v[188:191], v[110:113]
	v_mfma_f32_16x16x32_bf16 v[102:105], v[152:155], v[184:187], v[102:105]
	v_mfma_f32_16x16x32_bf16 v[102:105], v[156:159], v[188:191], v[102:105]
	v_mfma_f32_16x16x32_bf16 v[94:97], v[144:147], v[192:195], v[94:97]
	v_mfma_f32_16x16x32_bf16 v[94:97], v[148:151], v[196:199], v[94:97]
	v_mfma_f32_16x16x32_bf16 v[86:89], v[152:155], v[192:195], v[86:89]
	v_mfma_f32_16x16x32_bf16 v[86:89], v[156:159], v[196:199], v[86:89]
	v_mfma_f32_16x16x32_bf16 v[78:81], v[144:147], v[200:203], v[78:81]
	v_mfma_f32_16x16x32_bf16 v[78:81], v[148:151], v[204:207], v[78:81]
	v_mfma_f32_16x16x32_bf16 v[70:73], v[152:155], v[200:203], v[70:73]
	v_mfma_f32_16x16x32_bf16 v[70:73], v[156:159], v[204:207], v[70:73]
	s_setprio 0
	s_setprio 1
	v_mfma_f32_16x16x32_bf16 v[122:125], v[160:163], v[176:179], v[122:125]
	v_mfma_f32_16x16x32_bf16 v[122:125], v[164:167], v[180:183], v[122:125]
	v_mfma_f32_16x16x32_bf16 v[114:117], v[168:171], v[176:179], v[114:117]
	v_mfma_f32_16x16x32_bf16 v[114:117], v[172:175], v[180:183], v[114:117]
	v_mfma_f32_16x16x32_bf16 v[106:109], v[160:163], v[184:187], v[106:109]
	v_mfma_f32_16x16x32_bf16 v[106:109], v[164:167], v[188:191], v[106:109]
	v_mfma_f32_16x16x32_bf16 v[98:101], v[168:171], v[184:187], v[98:101]
	v_mfma_f32_16x16x32_bf16 v[98:101], v[172:175], v[188:191], v[98:101]
	s_setprio 3
	s_barrier
	v_mfma_f32_16x16x32_bf16 v[90:93], v[160:163], v[192:195], v[90:93]
	v_mfma_f32_16x16x32_bf16 v[90:93], v[164:167], v[196:199], v[90:93]
	v_mfma_f32_16x16x32_bf16 v[82:85], v[168:171], v[192:195], v[82:85]
	v_mfma_f32_16x16x32_bf16 v[82:85], v[172:175], v[196:199], v[82:85]
	v_mfma_f32_16x16x32_bf16 v[74:77], v[160:163], v[200:203], v[74:77]
	v_mfma_f32_16x16x32_bf16 v[74:77], v[164:167], v[204:207], v[74:77]
	v_mfma_f32_16x16x32_bf16 v[66:69], v[168:171], v[200:203], v[66:69]
	v_mfma_f32_16x16x32_bf16 v[66:69], v[172:175], v[204:207], v[66:69]
	s_setprio 0
	s_add_i32 s34, s34, s47
	v_lshl_add_u64 v[138:139], s[26:27], 0, v[0:1]
	s_mov_b32 m0, s34
	ds_read_b128 v[176:179], v143 offset:16384
	ds_read_b128 v[180:183], v143 offset:17408
	ds_read_b128 v[184:187], v143 offset:18432
	ds_read_b128 v[188:191], v143 offset:19456
	ds_read_b128 v[192:195], v143 offset:20480
	ds_read_b128 v[196:199], v143 offset:21504
	ds_read_b128 v[200:203], v143 offset:22528
	ds_read_b128 v[204:207], v143 offset:23552
	global_load_lds_dwordx4 v[138:139], off
	s_add_i32 m0, s34, 0x2000
	s_add_u32 s34, s26, 0x40000
	v_lshl_add_u64 v[208:209], s[26:27], 0, v[130:131]
	s_addc_u32 s35, s27, 0
	s_add_i32 s40, s40, s47
	global_load_lds_dwordx4 v[208:209], off
	v_lshl_add_u64 v[222:223], s[34:35], 0, v[0:1]
	s_mov_b32 m0, s40
	v_lshl_add_u64 v[224:225], s[30:31], 0, v[130:131]
	global_load_lds_dwordx4 v[222:223], off
	v_lshl_add_u64 v[222:223], s[34:35], 0, v[130:131]
	s_add_i32 m0, s40, 0x2000
	s_nop 0
	global_load_lds_dwordx4 v[222:223], off
	v_lshl_add_u64 v[222:223], s[30:31], 0, v[0:1]
	s_mov_b32 m0, s53
	s_nop 0
	global_load_lds_dwordx4 v[222:223], off
	s_mov_b32 m0, s64
	s_nop 0
	global_load_lds_dwordx4 v[224:225], off
	s_waitcnt vmcnt(8)
	s_waitcnt lgkmcnt(0)
	s_barrier
	s_setprio 1
	s_waitcnt lgkmcnt(0)
	v_mfma_f32_16x16x32_bf16 v[62:65], v[144:147], v[176:179], v[62:65]
	v_mfma_f32_16x16x32_bf16 v[62:65], v[148:151], v[180:183], v[62:65]
	v_mfma_f32_16x16x32_bf16 v[54:57], v[152:155], v[176:179], v[54:57]
	v_mfma_f32_16x16x32_bf16 v[54:57], v[156:159], v[180:183], v[54:57]
	v_mfma_f32_16x16x32_bf16 v[46:49], v[144:147], v[184:187], v[46:49]
	v_mfma_f32_16x16x32_bf16 v[46:49], v[148:151], v[188:191], v[46:49]
	v_mfma_f32_16x16x32_bf16 v[38:41], v[152:155], v[184:187], v[38:41]
	v_mfma_f32_16x16x32_bf16 v[38:41], v[156:159], v[188:191], v[38:41]
	v_mfma_f32_16x16x32_bf16 v[30:33], v[144:147], v[192:195], v[30:33]
	v_mfma_f32_16x16x32_bf16 v[30:33], v[148:151], v[196:199], v[30:33]
	v_mfma_f32_16x16x32_bf16 v[22:25], v[152:155], v[192:195], v[22:25]
	v_mfma_f32_16x16x32_bf16 v[22:25], v[156:159], v[196:199], v[22:25]
	v_mfma_f32_16x16x32_bf16 v[14:17], v[144:147], v[200:203], v[14:17]
	v_mfma_f32_16x16x32_bf16 v[14:17], v[148:151], v[204:207], v[14:17]
	v_mfma_f32_16x16x32_bf16 v[6:9], v[152:155], v[200:203], v[6:9]
	v_mfma_f32_16x16x32_bf16 v[6:9], v[156:159], v[204:207], v[6:9]
	s_setprio 0
	s_setprio 1
	v_mfma_f32_16x16x32_bf16 v[58:61], v[160:163], v[176:179], v[58:61]
	v_mfma_f32_16x16x32_bf16 v[58:61], v[164:167], v[180:183], v[58:61]
	v_mfma_f32_16x16x32_bf16 v[50:53], v[168:171], v[176:179], v[50:53]
	v_mfma_f32_16x16x32_bf16 v[50:53], v[172:175], v[180:183], v[50:53]
	v_mfma_f32_16x16x32_bf16 v[42:45], v[160:163], v[184:187], v[42:45]
	v_mfma_f32_16x16x32_bf16 v[42:45], v[164:167], v[188:191], v[42:45]
	v_mfma_f32_16x16x32_bf16 v[34:37], v[168:171], v[184:187], v[34:37]
	v_mfma_f32_16x16x32_bf16 v[34:37], v[172:175], v[188:191], v[34:37]
	s_setprio 3
	s_barrier
	v_mfma_f32_16x16x32_bf16 v[26:29], v[160:163], v[192:195], v[26:29]
	v_mfma_f32_16x16x32_bf16 v[26:29], v[164:167], v[196:199], v[26:29]
	v_mfma_f32_16x16x32_bf16 v[18:21], v[168:171], v[192:195], v[18:21]
	v_mfma_f32_16x16x32_bf16 v[18:21], v[172:175], v[196:199], v[18:21]
	v_mfma_f32_16x16x32_bf16 v[10:13], v[160:163], v[200:203], v[10:13]
	v_mfma_f32_16x16x32_bf16 v[10:13], v[164:167], v[204:207], v[10:13]
	v_mfma_f32_16x16x32_bf16 v[2:5], v[168:171], v[200:203], v[2:5]
	v_mfma_f32_16x16x32_bf16 v[2:5], v[172:175], v[204:207], v[2:5]
	s_setprio 0
	s_add_i32 s34, 0, 0x18000
	s_add_i32 s35, 0, 0x1c000
	v_add_u32_e32 v156, s34, v141
	v_add_u32_e32 v172, s35, v141
	ds_read_b128 v[144:147], v156
	ds_read_b128 v[148:151], v156 offset:1024
	ds_read_b128 v[152:155], v156 offset:2048
	ds_read_b128 v[156:159], v156 offset:3072
	ds_read_b128 v[160:163], v172
	ds_read_b128 v[164:167], v172 offset:1024
	ds_read_b128 v[168:171], v172 offset:2048
	ds_read_b128 v[172:175], v172 offset:3072
	s_add_u32 s30, s30, 0x40000
	s_addc_u32 s31, s31, 0
	s_mov_b32 m0, s65
	v_lshl_add_u64 v[226:227], s[30:31], 0, v[0:1]
	ds_read_b128 v[176:179], v143 offset:32768
	ds_read_b128 v[180:183], v143 offset:33792
	ds_read_b128 v[184:187], v143 offset:34816
	ds_read_b128 v[188:191], v143 offset:35840
	ds_read_b128 v[192:195], v143 offset:36864
	ds_read_b128 v[196:199], v143 offset:37888
	ds_read_b128 v[200:203], v143 offset:38912
	ds_read_b128 v[204:207], v143 offset:39936
	global_load_lds_dwordx4 v[226:227], off
	v_lshl_add_u64 v[226:227], s[30:31], 0, v[130:131]
	s_mov_b32 m0, s68
	s_nop 0
	global_load_lds_dwordx4 v[226:227], off
	s_waitcnt vmcnt(8)
	s_waitcnt lgkmcnt(0)
	s_barrier
	s_setprio 1
	s_waitcnt lgkmcnt(0)
	v_mfma_f32_16x16x32_bf16 v[126:129], v[144:147], v[176:179], v[126:129]
	v_mfma_f32_16x16x32_bf16 v[126:129], v[148:151], v[180:183], v[126:129]
	v_mfma_f32_16x16x32_bf16 v[118:121], v[152:155], v[176:179], v[118:121]
	v_mfma_f32_16x16x32_bf16 v[118:121], v[156:159], v[180:183], v[118:121]
	v_mfma_f32_16x16x32_bf16 v[110:113], v[144:147], v[184:187], v[110:113]
	v_mfma_f32_16x16x32_bf16 v[110:113], v[148:151], v[188:191], v[110:113]
	v_mfma_f32_16x16x32_bf16 v[102:105], v[152:155], v[184:187], v[102:105]
	v_mfma_f32_16x16x32_bf16 v[102:105], v[156:159], v[188:191], v[102:105]
	v_mfma_f32_16x16x32_bf16 v[94:97], v[144:147], v[192:195], v[94:97]
	v_mfma_f32_16x16x32_bf16 v[94:97], v[148:151], v[196:199], v[94:97]
	v_mfma_f32_16x16x32_bf16 v[86:89], v[152:155], v[192:195], v[86:89]
	v_mfma_f32_16x16x32_bf16 v[86:89], v[156:159], v[196:199], v[86:89]
	v_mfma_f32_16x16x32_bf16 v[78:81], v[144:147], v[200:203], v[78:81]
	v_mfma_f32_16x16x32_bf16 v[78:81], v[148:151], v[204:207], v[78:81]
	v_mfma_f32_16x16x32_bf16 v[70:73], v[152:155], v[200:203], v[70:73]
	v_mfma_f32_16x16x32_bf16 v[70:73], v[156:159], v[204:207], v[70:73]
	s_setprio 0
	s_setprio 1
	v_mfma_f32_16x16x32_bf16 v[122:125], v[160:163], v[176:179], v[122:125]
	v_mfma_f32_16x16x32_bf16 v[122:125], v[164:167], v[180:183], v[122:125]
	v_mfma_f32_16x16x32_bf16 v[114:117], v[168:171], v[176:179], v[114:117]
	v_mfma_f32_16x16x32_bf16 v[114:117], v[172:175], v[180:183], v[114:117]
	v_mfma_f32_16x16x32_bf16 v[106:109], v[160:163], v[184:187], v[106:109]
	v_mfma_f32_16x16x32_bf16 v[106:109], v[164:167], v[188:191], v[106:109]
	v_mfma_f32_16x16x32_bf16 v[98:101], v[168:171], v[184:187], v[98:101]
	v_mfma_f32_16x16x32_bf16 v[98:101], v[172:175], v[188:191], v[98:101]
	s_setprio 3
	s_barrier
	v_mfma_f32_16x16x32_bf16 v[90:93], v[160:163], v[192:195], v[90:93]
	v_mfma_f32_16x16x32_bf16 v[90:93], v[164:167], v[196:199], v[90:93]
	v_mfma_f32_16x16x32_bf16 v[82:85], v[168:171], v[192:195], v[82:85]
	v_mfma_f32_16x16x32_bf16 v[82:85], v[172:175], v[196:199], v[82:85]
	v_mfma_f32_16x16x32_bf16 v[74:77], v[160:163], v[200:203], v[74:77]
	v_mfma_f32_16x16x32_bf16 v[74:77], v[164:167], v[204:207], v[74:77]
	v_mfma_f32_16x16x32_bf16 v[66:69], v[168:171], v[200:203], v[66:69]
	v_mfma_f32_16x16x32_bf16 v[66:69], v[172:175], v[204:207], v[66:69]
	s_setprio 0
	s_add_i32 s30, s34, s47
	v_lshl_add_u64 v[138:139], v[138:139], 0, s[22:23]
	s_mov_b32 m0, s30
	ds_read_b128 v[176:179], v143 offset:49152
	ds_read_b128 v[180:183], v143 offset:50176
	ds_read_b128 v[184:187], v143 offset:51200
	ds_read_b128 v[188:191], v143 offset:52224
	ds_read_b128 v[192:195], v143 offset:53248
	ds_read_b128 v[196:199], v143 offset:54272
	ds_read_b128 v[200:203], v143 offset:55296
	ds_read_b128 v[204:207], v143 offset:56320
	global_load_lds_dwordx4 v[138:139], off
	s_add_i32 m0, s30, 0x2000
	s_add_u32 s26, s26, 0x40080
	v_lshl_add_u64 v[138:139], v[208:209], 0, s[22:23]
	s_addc_u32 s27, s27, 0
	s_add_i32 s30, s35, s47
	global_load_lds_dwordx4 v[138:139], off
	v_lshl_add_u64 v[138:139], s[26:27], 0, v[0:1]
	s_mov_b32 m0, s30
	s_nop 0
	global_load_lds_dwordx4 v[138:139], off
	v_lshl_add_u64 v[138:139], s[26:27], 0, v[130:131]
	s_add_i32 m0, s30, 0x2000
	s_nop 0
	global_load_lds_dwordx4 v[138:139], off
	v_lshl_add_u64 v[138:139], v[222:223], 0, s[22:23]
	s_mov_b32 m0, s69
	s_nop 0
	global_load_lds_dwordx4 v[138:139], off
	v_lshl_add_u64 v[138:139], v[224:225], 0, s[22:23]
	s_mov_b32 m0, s70
	s_nop 0
	global_load_lds_dwordx4 v[138:139], off
	s_waitcnt vmcnt(8)
	s_waitcnt lgkmcnt(0)
	s_barrier
	s_setprio 1
	s_waitcnt lgkmcnt(0)
	v_mfma_f32_16x16x32_bf16 v[62:65], v[144:147], v[176:179], v[62:65]
	v_mfma_f32_16x16x32_bf16 v[62:65], v[148:151], v[180:183], v[62:65]
	v_mfma_f32_16x16x32_bf16 v[54:57], v[152:155], v[176:179], v[54:57]
	v_mfma_f32_16x16x32_bf16 v[54:57], v[156:159], v[180:183], v[54:57]
	v_mfma_f32_16x16x32_bf16 v[46:49], v[144:147], v[184:187], v[46:49]
	v_mfma_f32_16x16x32_bf16 v[46:49], v[148:151], v[188:191], v[46:49]
	v_mfma_f32_16x16x32_bf16 v[38:41], v[152:155], v[184:187], v[38:41]
	v_mfma_f32_16x16x32_bf16 v[38:41], v[156:159], v[188:191], v[38:41]
	v_mfma_f32_16x16x32_bf16 v[30:33], v[144:147], v[192:195], v[30:33]
	v_mfma_f32_16x16x32_bf16 v[30:33], v[148:151], v[196:199], v[30:33]
	v_mfma_f32_16x16x32_bf16 v[22:25], v[152:155], v[192:195], v[22:25]
	v_mfma_f32_16x16x32_bf16 v[22:25], v[156:159], v[196:199], v[22:25]
	v_mfma_f32_16x16x32_bf16 v[14:17], v[144:147], v[200:203], v[14:17]
	v_mfma_f32_16x16x32_bf16 v[14:17], v[148:151], v[204:207], v[14:17]
	v_mfma_f32_16x16x32_bf16 v[6:9], v[152:155], v[200:203], v[6:9]
	v_mfma_f32_16x16x32_bf16 v[6:9], v[156:159], v[204:207], v[6:9]
	s_setprio 0
	s_setprio 1
	v_mfma_f32_16x16x32_bf16 v[58:61], v[160:163], v[176:179], v[58:61]
	v_mfma_f32_16x16x32_bf16 v[58:61], v[164:167], v[180:183], v[58:61]
	v_mfma_f32_16x16x32_bf16 v[50:53], v[168:171], v[176:179], v[50:53]
	v_mfma_f32_16x16x32_bf16 v[50:53], v[172:175], v[180:183], v[50:53]
	v_mfma_f32_16x16x32_bf16 v[42:45], v[160:163], v[184:187], v[42:45]
	v_mfma_f32_16x16x32_bf16 v[42:45], v[164:167], v[188:191], v[42:45]
	v_mfma_f32_16x16x32_bf16 v[34:37], v[168:171], v[184:187], v[34:37]
	v_mfma_f32_16x16x32_bf16 v[34:37], v[172:175], v[188:191], v[34:37]
	s_setprio 3
	s_barrier
	v_mfma_f32_16x16x32_bf16 v[26:29], v[160:163], v[192:195], v[26:29]
	v_mfma_f32_16x16x32_bf16 v[26:29], v[164:167], v[196:199], v[26:29]
	v_mfma_f32_16x16x32_bf16 v[18:21], v[168:171], v[192:195], v[18:21]
	v_mfma_f32_16x16x32_bf16 v[18:21], v[172:175], v[196:199], v[18:21]
	v_mfma_f32_16x16x32_bf16 v[10:13], v[160:163], v[200:203], v[10:13]
	v_mfma_f32_16x16x32_bf16 v[10:13], v[164:167], v[204:207], v[10:13]
	v_mfma_f32_16x16x32_bf16 v[2:5], v[168:171], v[200:203], v[2:5]
	v_mfma_f32_16x16x32_bf16 v[2:5], v[172:175], v[204:207], v[2:5]
	s_setprio 0
	s_add_i32 s37, s37, 2
	s_add_u32 s16, s16, 0x100
	s_addc_u32 s17, s17, 0
	s_add_u32 s29, s29, 0x100
	s_addc_u32 s36, s36, 0
	s_cmp_gt_u32 s37, 13
	s_cbranch_scc0 .LBB0_143
	s_and_b64 vcc, exec, s[2:3]
	s_cbranch_vccz .LBB0_146
	s_barrier

.LBB0_233:
	s_add_u32 s4, s0, 0xfffc0080
	s_addc_u32 s5, s1, -1
	s_add_i32 s18, 0, 0x10000
	s_cmp_eq_u32 s17, 12
	s_cselect_b32 s9, s3, s5
	s_cselect_b32 s8, s11, s4
	v_add_u32_e32 v0, s18, v191
	s_cselect_b32 s5, s12, s15
	s_cselect_b32 s4, s13, s14
	s_add_i32 s25, 0, 0x14000
	ds_read_b128 v[2:5], v0
	ds_read_b128 v[6:9], v0 offset:1024
	ds_read_b128 v[10:13], v0 offset:2048
	ds_read_b128 v[14:17], v0 offset:3072
	v_add_u32_e32 v0, s25, v191
	ds_read_b128 v[146:149], v0
	ds_read_b128 v[150:153], v0 offset:1024
	ds_read_b128 v[154:157], v0 offset:2048
	ds_read_b128 v[158:161], v0 offset:3072
	v_lshl_add_u64 v[230:231], s[0:1], 0, v[178:179]
	s_add_i32 m0, s65, 0xc000
	ds_read_b128 v[162:165], v200
	ds_read_b128 v[166:169], v200 offset:1024
	ds_read_b128 v[182:185], v200 offset:2048
	ds_read_b128 v[186:189], v200 offset:3072
	ds_read_b128 v[202:205], v200 offset:4096
	ds_read_b128 v[206:209], v200 offset:5120
	ds_read_b128 v[222:225], v200 offset:6144
	ds_read_b128 v[226:229], v200 offset:7168
	global_load_lds_dwordx4 v[230:231], off
	v_lshl_add_u64 v[230:231], s[0:1], 0, v[180:181]
	s_add_i32 m0, s65, 0xe000
	s_nop 0
	global_load_lds_dwordx4 v[230:231], off
	s_waitcnt vmcnt(8)
	s_waitcnt lgkmcnt(0)
	s_barrier
	s_setprio 1
	s_waitcnt lgkmcnt(0)
	v_mfma_f32_16x16x32_bf16 v[142:145], v[2:5], v[162:165], v[142:145]
	v_mfma_f32_16x16x32_bf16 v[142:145], v[6:9], v[166:169], v[142:145]
	v_mfma_f32_16x16x32_bf16 v[138:141], v[10:13], v[162:165], v[138:141]
	v_mfma_f32_16x16x32_bf16 v[138:141], v[14:17], v[166:169], v[138:141]
	v_mfma_f32_16x16x32_bf16 v[134:137], v[2:5], v[182:185], v[134:137]
	v_mfma_f32_16x16x32_bf16 v[134:137], v[6:9], v[186:189], v[134:137]
	v_mfma_f32_16x16x32_bf16 v[126:129], v[10:13], v[182:185], v[126:129]
	v_mfma_f32_16x16x32_bf16 v[126:129], v[14:17], v[186:189], v[126:129]
	v_mfma_f32_16x16x32_bf16 v[118:121], v[2:5], v[202:205], v[118:121]
	v_mfma_f32_16x16x32_bf16 v[118:121], v[6:9], v[206:209], v[118:121]
	v_mfma_f32_16x16x32_bf16 v[110:113], v[10:13], v[202:205], v[110:113]
	v_mfma_f32_16x16x32_bf16 v[110:113], v[14:17], v[206:209], v[110:113]
	v_mfma_f32_16x16x32_bf16 v[102:105], v[2:5], v[222:225], v[102:105]
	v_mfma_f32_16x16x32_bf16 v[102:105], v[6:9], v[226:229], v[102:105]
	v_mfma_f32_16x16x32_bf16 v[94:97], v[10:13], v[222:225], v[94:97]
	v_mfma_f32_16x16x32_bf16 v[94:97], v[14:17], v[226:229], v[94:97]
	s_setprio 0
	s_setprio 1
	v_mfma_f32_16x16x32_bf16 v[130:133], v[146:149], v[162:165], v[130:133]
	v_mfma_f32_16x16x32_bf16 v[130:133], v[150:153], v[166:169], v[130:133]
	v_mfma_f32_16x16x32_bf16 v[122:125], v[154:157], v[162:165], v[122:125]
	v_mfma_f32_16x16x32_bf16 v[122:125], v[158:161], v[166:169], v[122:125]
	v_mfma_f32_16x16x32_bf16 v[114:117], v[146:149], v[182:185], v[114:117]
	v_mfma_f32_16x16x32_bf16 v[114:117], v[150:153], v[186:189], v[114:117]
	v_mfma_f32_16x16x32_bf16 v[106:109], v[154:157], v[182:185], v[106:109]
	v_mfma_f32_16x16x32_bf16 v[106:109], v[158:161], v[186:189], v[106:109]
	s_setprio 3
	s_barrier
	v_mfma_f32_16x16x32_bf16 v[98:101], v[146:149], v[202:205], v[98:101]
	v_mfma_f32_16x16x32_bf16 v[98:101], v[150:153], v[206:209], v[98:101]
	v_mfma_f32_16x16x32_bf16 v[90:93], v[154:157], v[202:205], v[90:93]
	v_mfma_f32_16x16x32_bf16 v[90:93], v[158:161], v[206:209], v[90:93]
	v_mfma_f32_16x16x32_bf16 v[86:89], v[146:149], v[222:225], v[86:89]
	v_mfma_f32_16x16x32_bf16 v[86:89], v[150:153], v[226:229], v[86:89]
	v_mfma_f32_16x16x32_bf16 v[82:85], v[154:157], v[222:225], v[82:85]
	v_mfma_f32_16x16x32_bf16 v[82:85], v[158:161], v[226:229], v[82:85]
	s_setprio 0
	s_add_i32 s18, s18, s64
	v_lshl_add_u64 v[230:231], s[4:5], 0, v[172:173]
	s_mov_b32 m0, s18
	ds_read_b128 v[162:165], v200 offset:16384
	ds_read_b128 v[166:169], v200 offset:17408
	ds_read_b128 v[182:185], v200 offset:18432
	ds_read_b128 v[186:189], v200 offset:19456
	ds_read_b128 v[202:205], v200 offset:20480
	ds_read_b128 v[206:209], v200 offset:21504
	ds_read_b128 v[222:225], v200 offset:22528
	ds_read_b128 v[226:229], v200 offset:23552
	global_load_lds_dwordx4 v[230:231], off
	s_add_i32 m0, s18, 0x2000
	s_add_u32 s18, s4, 0x40000
	v_lshl_add_u64 v[232:233], s[4:5], 0, v[170:171]
	s_addc_u32 s19, s5, 0
	s_add_i32 s25, s25, s64
	global_load_lds_dwordx4 v[232:233], off
	v_lshl_add_u64 v[246:247], s[18:19], 0, v[172:173]
	s_mov_b32 m0, s25
	v_lshl_add_u64 v[248:249], s[8:9], 0, v[170:171]
	global_load_lds_dwordx4 v[246:247], off
	v_lshl_add_u64 v[246:247], s[18:19], 0, v[170:171]
	s_add_i32 m0, s25, 0x2000
	s_nop 0
	global_load_lds_dwordx4 v[246:247], off
	v_lshl_add_u64 v[246:247], s[8:9], 0, v[172:173]
	s_mov_b32 m0, s65
	s_nop 0
	global_load_lds_dwordx4 v[246:247], off
	s_mov_b32 m0, s68
	s_nop 0
	global_load_lds_dwordx4 v[248:249], off
	s_waitcnt vmcnt(8)
	s_waitcnt lgkmcnt(0)
	s_barrier
	s_setprio 1
	s_waitcnt lgkmcnt(0)
	v_mfma_f32_16x16x32_bf16 v[78:81], v[2:5], v[162:165], v[78:81]
	v_mfma_f32_16x16x32_bf16 v[74:77], v[10:13], v[162:165], v[74:77]
	v_mfma_f32_16x16x32_bf16 v[70:73], v[2:5], v[182:185], v[70:73]
	v_mfma_f32_16x16x32_bf16 v[62:65], v[10:13], v[182:185], v[62:65]
	v_mfma_f32_16x16x32_bf16 v[54:57], v[2:5], v[202:205], v[54:57]
	v_mfma_f32_16x16x32_bf16 v[46:49], v[10:13], v[202:205], v[46:49]
	v_mfma_f32_16x16x32_bf16 v[2:5], v[2:5], v[222:225], v[38:41]
	v_mfma_f32_16x16x32_bf16 v[78:81], v[6:9], v[166:169], v[78:81]
	v_mfma_f32_16x16x32_bf16 v[74:77], v[14:17], v[166:169], v[74:77]
	v_mfma_f32_16x16x32_bf16 v[70:73], v[6:9], v[186:189], v[70:73]
	v_mfma_f32_16x16x32_bf16 v[62:65], v[14:17], v[186:189], v[62:65]
	v_mfma_f32_16x16x32_bf16 v[54:57], v[6:9], v[206:209], v[54:57]
	v_mfma_f32_16x16x32_bf16 v[46:49], v[14:17], v[206:209], v[46:49]
	v_mfma_f32_16x16x32_bf16 v[2:5], v[6:9], v[226:229], v[2:5]
	v_mfma_f32_16x16x32_bf16 v[6:9], v[10:13], v[222:225], v[30:33]
	v_mfma_f32_16x16x32_bf16 v[6:9], v[14:17], v[226:229], v[6:9]
	s_setprio 0
	s_setprio 1
	v_mfma_f32_16x16x32_bf16 v[30:33], v[146:149], v[182:185], v[50:53]
	v_mfma_f32_16x16x32_bf16 v[50:53], v[150:153], v[186:189], v[30:33]
	v_mfma_f32_16x16x32_bf16 v[30:33], v[154:157], v[182:185], v[42:45]
	v_mfma_f32_16x16x32_bf16 v[42:45], v[158:161], v[186:189], v[30:33]
	v_mfma_f32_16x16x32_bf16 v[30:33], v[146:149], v[202:205], v[34:37]
	v_mfma_f32_16x16x32_bf16 v[26:29], v[154:157], v[202:205], v[26:29]
	v_mfma_f32_16x16x32_bf16 v[22:25], v[146:149], v[222:225], v[22:25]
	v_mfma_f32_16x16x32_bf16 v[18:21], v[154:157], v[222:225], v[18:21]
	s_setprio 3
	s_barrier
	v_mfma_f32_16x16x32_bf16 v[10:13], v[146:149], v[162:165], v[66:69]
	v_mfma_f32_16x16x32_bf16 v[14:17], v[154:157], v[162:165], v[58:61]
	v_mfma_f32_16x16x32_bf16 v[34:37], v[150:153], v[206:209], v[30:33]
	v_mfma_f32_16x16x32_bf16 v[26:29], v[158:161], v[206:209], v[26:29]
	v_mfma_f32_16x16x32_bf16 v[22:25], v[150:153], v[226:229], v[22:25]
	v_mfma_f32_16x16x32_bf16 v[18:21], v[158:161], v[226:229], v[18:21]
	v_mfma_f32_16x16x32_bf16 v[10:13], v[150:153], v[166:169], v[10:13]
	v_mfma_f32_16x16x32_bf16 v[14:17], v[158:161], v[166:169], v[14:17]
	s_setprio 0
	s_add_i32 s18, 0, 0x18000
	v_add_u32_e32 v0, s18, v191
	s_add_i32 s19, 0, 0x1c000
	ds_read_b128 v[30:33], v0
	ds_read_b128 v[38:41], v0 offset:1024
	ds_read_b128 v[58:61], v0 offset:2048
	ds_read_b128 v[66:69], v0 offset:3072
	v_add_u32_e32 v0, s19, v191
	ds_read_b128 v[146:149], v0
	ds_read_b128 v[150:153], v0 offset:1024
	ds_read_b128 v[154:157], v0 offset:2048
	ds_read_b128 v[158:161], v0 offset:3072
	s_add_u32 s8, s8, 0x40000
	s_addc_u32 s9, s9, 0
	s_mov_b32 m0, s69
	v_lshl_add_u64 v[250:251], s[8:9], 0, v[172:173]
	ds_read_b128 v[162:165], v200 offset:32768
	ds_read_b128 v[166:169], v200 offset:33792
	ds_read_b128 v[182:185], v200 offset:34816
	ds_read_b128 v[186:189], v200 offset:35840
	ds_read_b128 v[202:205], v200 offset:36864
	ds_read_b128 v[206:209], v200 offset:37888
	ds_read_b128 v[222:225], v200 offset:38912
	ds_read_b128 v[226:229], v200 offset:39936
	global_load_lds_dwordx4 v[250:251], off
	v_lshl_add_u64 v[250:251], s[8:9], 0, v[170:171]
	s_mov_b32 m0, s70
	s_nop 0
	global_load_lds_dwordx4 v[250:251], off
	s_waitcnt vmcnt(8)
	s_waitcnt lgkmcnt(0)
	s_barrier
	s_setprio 1
	s_waitcnt lgkmcnt(0)
	v_mfma_f32_16x16x32_bf16 v[142:145], v[30:33], v[162:165], v[142:145]
	v_mfma_f32_16x16x32_bf16 v[142:145], v[38:41], v[166:169], v[142:145]
	v_mfma_f32_16x16x32_bf16 v[138:141], v[58:61], v[162:165], v[138:141]
	v_mfma_f32_16x16x32_bf16 v[138:141], v[66:69], v[166:169], v[138:141]
	v_mfma_f32_16x16x32_bf16 v[134:137], v[30:33], v[182:185], v[134:137]
	v_mfma_f32_16x16x32_bf16 v[134:137], v[38:41], v[186:189], v[134:137]
	v_mfma_f32_16x16x32_bf16 v[126:129], v[58:61], v[182:185], v[126:129]
	v_mfma_f32_16x16x32_bf16 v[126:129], v[66:69], v[186:189], v[126:129]
	v_mfma_f32_16x16x32_bf16 v[118:121], v[30:33], v[202:205], v[118:121]
	v_mfma_f32_16x16x32_bf16 v[118:121], v[38:41], v[206:209], v[118:121]
	v_mfma_f32_16x16x32_bf16 v[110:113], v[58:61], v[202:205], v[110:113]
	v_mfma_f32_16x16x32_bf16 v[110:113], v[66:69], v[206:209], v[110:113]
	v_mfma_f32_16x16x32_bf16 v[102:105], v[30:33], v[222:225], v[102:105]
	v_mfma_f32_16x16x32_bf16 v[102:105], v[38:41], v[226:229], v[102:105]
	v_mfma_f32_16x16x32_bf16 v[94:97], v[58:61], v[222:225], v[94:97]
	v_mfma_f32_16x16x32_bf16 v[94:97], v[66:69], v[226:229], v[94:97]
	s_setprio 0
	s_setprio 1
	v_mfma_f32_16x16x32_bf16 v[130:133], v[146:149], v[162:165], v[130:133]
	v_mfma_f32_16x16x32_bf16 v[130:133], v[150:153], v[166:169], v[130:133]
	v_mfma_f32_16x16x32_bf16 v[122:125], v[154:157], v[162:165], v[122:125]
	v_mfma_f32_16x16x32_bf16 v[122:125], v[158:161], v[166:169], v[122:125]
	v_mfma_f32_16x16x32_bf16 v[114:117], v[146:149], v[182:185], v[114:117]
	v_mfma_f32_16x16x32_bf16 v[114:117], v[150:153], v[186:189], v[114:117]
	v_mfma_f32_16x16x32_bf16 v[106:109], v[154:157], v[182:185], v[106:109]
	v_mfma_f32_16x16x32_bf16 v[106:109], v[158:161], v[186:189], v[106:109]
	s_setprio 3
	s_barrier
	v_mfma_f32_16x16x32_bf16 v[98:101], v[146:149], v[202:205], v[98:101]
	v_mfma_f32_16x16x32_bf16 v[98:101], v[150:153], v[206:209], v[98:101]
	v_mfma_f32_16x16x32_bf16 v[90:93], v[154:157], v[202:205], v[90:93]
	v_mfma_f32_16x16x32_bf16 v[90:93], v[158:161], v[206:209], v[90:93]
	v_mfma_f32_16x16x32_bf16 v[86:89], v[146:149], v[222:225], v[86:89]
	v_mfma_f32_16x16x32_bf16 v[86:89], v[150:153], v[226:229], v[86:89]
	v_mfma_f32_16x16x32_bf16 v[82:85], v[154:157], v[222:225], v[82:85]
	v_mfma_f32_16x16x32_bf16 v[82:85], v[158:161], v[226:229], v[82:85]
	s_setprio 0
	s_add_i32 s8, s18, s64
	v_lshl_add_u64 v[230:231], v[230:231], 0, s[22:23]
	s_mov_b32 m0, s8
	ds_read_b128 v[162:165], v200 offset:49152
	ds_read_b128 v[166:169], v200 offset:50176
	ds_read_b128 v[182:185], v200 offset:51200
	ds_read_b128 v[186:189], v200 offset:52224
	ds_read_b128 v[202:205], v200 offset:53248
	ds_read_b128 v[206:209], v200 offset:54272
	ds_read_b128 v[222:225], v200 offset:55296
	ds_read_b128 v[226:229], v200 offset:56320
	global_load_lds_dwordx4 v[230:231], off
	s_add_i32 m0, s8, 0x2000
	s_add_u32 s4, s4, 0x40080
	v_lshl_add_u64 v[230:231], v[232:233], 0, s[22:23]
	s_addc_u32 s5, s5, 0
	s_add_i32 s8, s19, s64
	global_load_lds_dwordx4 v[230:231], off
	v_lshl_add_u64 v[230:231], s[4:5], 0, v[172:173]
	s_mov_b32 m0, s8
	s_nop 0
	global_load_lds_dwordx4 v[230:231], off
	v_lshl_add_u64 v[230:231], s[4:5], 0, v[170:171]
	s_add_i32 m0, s8, 0x2000
	s_nop 0
	global_load_lds_dwordx4 v[230:231], off
	v_lshl_add_u64 v[230:231], v[246:247], 0, s[22:23]
	s_mov_b32 m0, s94
	s_nop 0
	global_load_lds_dwordx4 v[230:231], off
	v_lshl_add_u64 v[230:231], v[248:249], 0, s[22:23]
	s_mov_b32 m0, s95
	s_nop 0
	global_load_lds_dwordx4 v[230:231], off
	s_waitcnt vmcnt(8)
	s_waitcnt lgkmcnt(0)
	s_barrier
	s_setprio 1
	s_waitcnt lgkmcnt(0)
	v_mfma_f32_16x16x32_bf16 v[78:81], v[30:33], v[162:165], v[78:81]
	v_mfma_f32_16x16x32_bf16 v[70:73], v[30:33], v[182:185], v[70:73]
	v_mfma_f32_16x16x32_bf16 v[54:57], v[30:33], v[202:205], v[54:57]
	v_mfma_f32_16x16x32_bf16 v[2:5], v[30:33], v[222:225], v[2:5]
	v_mfma_f32_16x16x32_bf16 v[78:81], v[38:41], v[166:169], v[78:81]
	v_mfma_f32_16x16x32_bf16 v[74:77], v[58:61], v[162:165], v[74:77]
	v_mfma_f32_16x16x32_bf16 v[70:73], v[38:41], v[186:189], v[70:73]
	v_mfma_f32_16x16x32_bf16 v[62:65], v[58:61], v[182:185], v[62:65]
	v_mfma_f32_16x16x32_bf16 v[54:57], v[38:41], v[206:209], v[54:57]
	v_mfma_f32_16x16x32_bf16 v[46:49], v[58:61], v[202:205], v[46:49]
	v_mfma_f32_16x16x32_bf16 v[38:41], v[38:41], v[226:229], v[2:5]
	v_mfma_f32_16x16x32_bf16 v[2:5], v[58:61], v[222:225], v[6:9]
	v_mfma_f32_16x16x32_bf16 v[74:77], v[66:69], v[166:169], v[74:77]
	v_mfma_f32_16x16x32_bf16 v[62:65], v[66:69], v[186:189], v[62:65]
	v_mfma_f32_16x16x32_bf16 v[46:49], v[66:69], v[206:209], v[46:49]
	v_mfma_f32_16x16x32_bf16 v[30:33], v[66:69], v[226:229], v[2:5]
	s_setprio 0
	s_setprio 1
	v_mfma_f32_16x16x32_bf16 v[2:5], v[146:149], v[162:165], v[10:13]
	v_mfma_f32_16x16x32_bf16 v[66:69], v[150:153], v[166:169], v[2:5]
	v_mfma_f32_16x16x32_bf16 v[2:5], v[154:157], v[162:165], v[14:17]
	v_mfma_f32_16x16x32_bf16 v[58:61], v[158:161], v[166:169], v[2:5]
	v_mfma_f32_16x16x32_bf16 v[2:5], v[146:149], v[182:185], v[50:53]
	v_mfma_f32_16x16x32_bf16 v[50:53], v[150:153], v[186:189], v[2:5]
	v_mfma_f32_16x16x32_bf16 v[2:5], v[154:157], v[182:185], v[42:45]
	v_mfma_f32_16x16x32_bf16 v[42:45], v[158:161], v[186:189], v[2:5]
	s_setprio 3
	s_barrier
	v_mfma_f32_16x16x32_bf16 v[2:5], v[146:149], v[202:205], v[34:37]
	v_mfma_f32_16x16x32_bf16 v[34:37], v[150:153], v[206:209], v[2:5]
	v_mfma_f32_16x16x32_bf16 v[2:5], v[154:157], v[202:205], v[26:29]
	v_mfma_f32_16x16x32_bf16 v[26:29], v[158:161], v[206:209], v[2:5]
	v_mfma_f32_16x16x32_bf16 v[2:5], v[146:149], v[222:225], v[22:25]
	v_mfma_f32_16x16x32_bf16 v[22:25], v[150:153], v[226:229], v[2:5]
	v_mfma_f32_16x16x32_bf16 v[2:5], v[154:157], v[222:225], v[18:21]
	v_mfma_f32_16x16x32_bf16 v[18:21], v[158:161], v[226:229], v[2:5]
	s_setprio 0
	s_add_i32 s17, s17, 2
	s_add_u32 s0, s0, 0x100
	s_addc_u32 s1, s1, 0
	s_add_u32 s14, s14, 0x100
	s_addc_u32 s15, s15, 0
	s_cmp_gt_u32 s17, 13
	s_cbranch_scc0 .LBB0_233
	s_and_b64 vcc, exec, s[78:79]
	s_cbranch_vccz .LBB0_236
	s_barrier

.LBB0_707:
	s_add_i32 s34, s68, 2
	s_add_u32 s35, s0, 0x80
	s_addc_u32 s69, s1, 0
	s_add_i32 s84, 0, 0x10000
	s_cmp_eq_u32 s96, s68
	s_cselect_b32 s69, s53, s69
	s_cselect_b32 s68, s52, s35
	s_cselect_b32 s89, s65, vcc_hi
	s_cselect_b32 s88, s64, vcc_lo
	s_add_i32 s35, 0, 0x14000
	v_add_u32_e32 v142, s84, v212
	v_add_u32_e32 v158, s35, v212
	ds_read_b128 v[130:133], v142
	ds_read_b128 v[134:137], v142 offset:1024
	ds_read_b128 v[138:141], v142 offset:2048
	ds_read_b128 v[142:145], v142 offset:3072
	ds_read_b128 v[146:149], v158
	ds_read_b128 v[150:153], v158 offset:1024
	ds_read_b128 v[154:157], v158 offset:2048
	ds_read_b128 v[158:161], v158 offset:3072
	v_lshl_add_u64 v[194:195], s[0:1], 0, v[224:225]
	s_add_i32 m0, s28, 0xc000
	ds_read_b128 v[162:165], v245
	ds_read_b128 v[166:169], v245 offset:1024
	ds_read_b128 v[170:173], v245 offset:2048
	ds_read_b128 v[174:177], v245 offset:3072
	ds_read_b128 v[178:181], v245 offset:4096
	ds_read_b128 v[182:185], v245 offset:5120
	ds_read_b128 v[186:189], v245 offset:6144
	ds_read_b128 v[190:193], v245 offset:7168
	global_load_lds_dwordx4 v[194:195], off
	v_lshl_add_u64 v[194:195], s[0:1], 0, v[226:227]
	s_add_i32 m0, s28, 0xe000
	s_nop 0
	global_load_lds_dwordx4 v[194:195], off
	s_waitcnt vmcnt(8)
	s_waitcnt lgkmcnt(0)
	s_barrier
	s_setprio 1
	s_waitcnt lgkmcnt(0)
	v_mfma_f32_16x16x32_bf16 v[126:129], v[130:133], v[162:165], v[126:129]
	v_mfma_f32_16x16x32_bf16 v[126:129], v[134:137], v[166:169], v[126:129]
	v_mfma_f32_16x16x32_bf16 v[122:125], v[138:141], v[162:165], v[122:125]
	v_mfma_f32_16x16x32_bf16 v[122:125], v[142:145], v[166:169], v[122:125]
	v_mfma_f32_16x16x32_bf16 v[114:117], v[130:133], v[170:173], v[114:117]
	v_mfma_f32_16x16x32_bf16 v[114:117], v[134:137], v[174:177], v[114:117]
	v_mfma_f32_16x16x32_bf16 v[106:109], v[138:141], v[170:173], v[106:109]
	v_mfma_f32_16x16x32_bf16 v[106:109], v[142:145], v[174:177], v[106:109]
	v_mfma_f32_16x16x32_bf16 v[98:101], v[130:133], v[178:181], v[98:101]
	v_mfma_f32_16x16x32_bf16 v[98:101], v[134:137], v[182:185], v[98:101]
	v_mfma_f32_16x16x32_bf16 v[90:93], v[138:141], v[178:181], v[90:93]
	v_mfma_f32_16x16x32_bf16 v[90:93], v[142:145], v[182:185], v[90:93]
	v_mfma_f32_16x16x32_bf16 v[82:85], v[130:133], v[186:189], v[82:85]
	v_mfma_f32_16x16x32_bf16 v[82:85], v[134:137], v[190:193], v[82:85]
	v_mfma_f32_16x16x32_bf16 v[74:77], v[138:141], v[186:189], v[74:77]
	v_mfma_f32_16x16x32_bf16 v[74:77], v[142:145], v[190:193], v[74:77]
	s_setprio 0
	s_setprio 1
	v_mfma_f32_16x16x32_bf16 v[118:121], v[146:149], v[162:165], v[118:121]
	v_mfma_f32_16x16x32_bf16 v[118:121], v[150:153], v[166:169], v[118:121]
	v_mfma_f32_16x16x32_bf16 v[110:113], v[154:157], v[162:165], v[110:113]
	v_mfma_f32_16x16x32_bf16 v[110:113], v[158:161], v[166:169], v[110:113]
	v_mfma_f32_16x16x32_bf16 v[102:105], v[146:149], v[170:173], v[102:105]
	v_mfma_f32_16x16x32_bf16 v[102:105], v[150:153], v[174:177], v[102:105]
	v_mfma_f32_16x16x32_bf16 v[94:97], v[154:157], v[170:173], v[94:97]
	v_mfma_f32_16x16x32_bf16 v[94:97], v[158:161], v[174:177], v[94:97]
	s_setprio 3
	s_barrier
	v_mfma_f32_16x16x32_bf16 v[86:89], v[146:149], v[178:181], v[86:89]
	v_mfma_f32_16x16x32_bf16 v[86:89], v[150:153], v[182:185], v[86:89]
	v_mfma_f32_16x16x32_bf16 v[78:81], v[154:157], v[178:181], v[78:81]
	v_mfma_f32_16x16x32_bf16 v[78:81], v[158:161], v[182:185], v[78:81]
	v_mfma_f32_16x16x32_bf16 v[70:73], v[146:149], v[186:189], v[70:73]
	v_mfma_f32_16x16x32_bf16 v[70:73], v[150:153], v[190:193], v[70:73]
	v_mfma_f32_16x16x32_bf16 v[66:69], v[154:157], v[186:189], v[66:69]
	v_mfma_f32_16x16x32_bf16 v[66:69], v[158:161], v[190:193], v[66:69]
	s_setprio 0
	s_add_i32 s84, s84, s19
	v_lshl_add_u64 v[194:195], s[88:89], 0, v[0:1]
	s_mov_b32 m0, s84
	ds_read_b128 v[162:165], v245 offset:16384
	ds_read_b128 v[166:169], v245 offset:17408
	ds_read_b128 v[170:173], v245 offset:18432
	ds_read_b128 v[174:177], v245 offset:19456
	ds_read_b128 v[178:181], v245 offset:20480
	ds_read_b128 v[182:185], v245 offset:21504
	ds_read_b128 v[186:189], v245 offset:22528
	ds_read_b128 v[190:193], v245 offset:23552
	global_load_lds_dwordx4 v[194:195], off
	s_add_i32 m0, s84, 0x2000
	v_lshl_add_u64 v[196:197], s[88:89], 0, v[222:223]
	s_add_u32 s88, s88, s2
	s_addc_u32 s89, s89, 0
	s_add_i32 s35, s35, s19
	global_load_lds_dwordx4 v[196:197], off
	v_lshl_add_u64 v[198:199], s[88:89], 0, v[0:1]
	s_mov_b32 m0, s35
	v_lshl_add_u64 v[200:201], s[88:89], 0, v[222:223]
	global_load_lds_dwordx4 v[198:199], off
	s_add_i32 m0, s35, 0x2000
	v_lshl_add_u64 v[202:203], s[68:69], 0, v[0:1]
	global_load_lds_dwordx4 v[200:201], off
	s_mov_b32 m0, s28
	v_lshl_add_u64 v[204:205], s[68:69], 0, v[222:223]
	global_load_lds_dwordx4 v[202:203], off
	s_mov_b32 m0, s29
	s_nop 0
	global_load_lds_dwordx4 v[204:205], off
	s_waitcnt vmcnt(8)
	s_waitcnt lgkmcnt(0)
	s_barrier
	s_setprio 1
	s_waitcnt lgkmcnt(0)
	v_mfma_f32_16x16x32_bf16 v[62:65], v[130:133], v[162:165], v[62:65]
	v_mfma_f32_16x16x32_bf16 v[62:65], v[134:137], v[166:169], v[62:65]
	v_mfma_f32_16x16x32_bf16 v[58:61], v[138:141], v[162:165], v[58:61]
	v_mfma_f32_16x16x32_bf16 v[58:61], v[142:145], v[166:169], v[58:61]
	v_mfma_f32_16x16x32_bf16 v[50:53], v[130:133], v[170:173], v[50:53]
	v_mfma_f32_16x16x32_bf16 v[50:53], v[134:137], v[174:177], v[50:53]
	v_mfma_f32_16x16x32_bf16 v[42:45], v[138:141], v[170:173], v[42:45]
	v_mfma_f32_16x16x32_bf16 v[42:45], v[142:145], v[174:177], v[42:45]
	v_mfma_f32_16x16x32_bf16 v[34:37], v[130:133], v[178:181], v[34:37]
	v_mfma_f32_16x16x32_bf16 v[34:37], v[134:137], v[182:185], v[34:37]
	v_mfma_f32_16x16x32_bf16 v[26:29], v[138:141], v[178:181], v[26:29]
	v_mfma_f32_16x16x32_bf16 v[26:29], v[142:145], v[182:185], v[26:29]
	v_mfma_f32_16x16x32_bf16 v[18:21], v[130:133], v[186:189], v[18:21]
	v_mfma_f32_16x16x32_bf16 v[18:21], v[134:137], v[190:193], v[18:21]
	v_mfma_f32_16x16x32_bf16 v[10:13], v[138:141], v[186:189], v[10:13]
	v_mfma_f32_16x16x32_bf16 v[10:13], v[142:145], v[190:193], v[10:13]
	s_setprio 0
	s_setprio 1
	v_mfma_f32_16x16x32_bf16 v[54:57], v[146:149], v[162:165], v[54:57]
	v_mfma_f32_16x16x32_bf16 v[54:57], v[150:153], v[166:169], v[54:57]
	v_mfma_f32_16x16x32_bf16 v[46:49], v[154:157], v[162:165], v[46:49]
	v_mfma_f32_16x16x32_bf16 v[46:49], v[158:161], v[166:169], v[46:49]
	v_mfma_f32_16x16x32_bf16 v[38:41], v[146:149], v[170:173], v[38:41]
	v_mfma_f32_16x16x32_bf16 v[38:41], v[150:153], v[174:177], v[38:41]
	v_mfma_f32_16x16x32_bf16 v[30:33], v[154:157], v[170:173], v[30:33]
	v_mfma_f32_16x16x32_bf16 v[30:33], v[158:161], v[174:177], v[30:33]
	s_setprio 3
	s_barrier
	v_mfma_f32_16x16x32_bf16 v[22:25], v[146:149], v[178:181], v[22:25]
	v_mfma_f32_16x16x32_bf16 v[22:25], v[150:153], v[182:185], v[22:25]
	v_mfma_f32_16x16x32_bf16 v[14:17], v[154:157], v[178:181], v[14:17]
	v_mfma_f32_16x16x32_bf16 v[14:17], v[158:161], v[182:185], v[14:17]
	v_mfma_f32_16x16x32_bf16 v[6:9], v[146:149], v[186:189], v[6:9]
	v_mfma_f32_16x16x32_bf16 v[6:9], v[150:153], v[190:193], v[6:9]
	v_mfma_f32_16x16x32_bf16 v[2:5], v[154:157], v[186:189], v[2:5]
	v_mfma_f32_16x16x32_bf16 v[2:5], v[158:161], v[190:193], v[2:5]
	s_setprio 0
	s_add_i32 s35, 0, 0x18000
	s_add_i32 s84, 0, 0x1c000
	v_add_u32_e32 v142, s35, v212
	v_add_u32_e32 v158, s84, v212
	ds_read_b128 v[130:133], v142
	ds_read_b128 v[134:137], v142 offset:1024
	ds_read_b128 v[138:141], v142 offset:2048
	ds_read_b128 v[142:145], v142 offset:3072
	ds_read_b128 v[146:149], v158
	ds_read_b128 v[150:153], v158 offset:1024
	ds_read_b128 v[154:157], v158 offset:2048
	ds_read_b128 v[158:161], v158 offset:3072
	s_add_u32 s68, s68, s2
	s_addc_u32 s69, s69, 0
	s_mov_b32 m0, s25
	v_lshl_add_u64 v[206:207], s[68:69], 0, v[0:1]
	ds_read_b128 v[162:165], v245 offset:32768
	ds_read_b128 v[166:169], v245 offset:33792
	ds_read_b128 v[170:173], v245 offset:34816
	ds_read_b128 v[174:177], v245 offset:35840
	ds_read_b128 v[178:181], v245 offset:36864
	ds_read_b128 v[182:185], v245 offset:37888
	ds_read_b128 v[186:189], v245 offset:38912
	ds_read_b128 v[190:193], v245 offset:39936
	global_load_lds_dwordx4 v[206:207], off
	v_lshl_add_u64 v[206:207], s[68:69], 0, v[222:223]
	s_mov_b32 m0, s36
	s_nop 0
	global_load_lds_dwordx4 v[206:207], off
	s_waitcnt vmcnt(8)
	s_waitcnt lgkmcnt(0)
	s_barrier
	s_setprio 1
	s_waitcnt lgkmcnt(0)
	v_mfma_f32_16x16x32_bf16 v[126:129], v[130:133], v[162:165], v[126:129]
	v_mfma_f32_16x16x32_bf16 v[126:129], v[134:137], v[166:169], v[126:129]
	v_mfma_f32_16x16x32_bf16 v[122:125], v[138:141], v[162:165], v[122:125]
	v_mfma_f32_16x16x32_bf16 v[122:125], v[142:145], v[166:169], v[122:125]
	v_mfma_f32_16x16x32_bf16 v[114:117], v[130:133], v[170:173], v[114:117]
	v_mfma_f32_16x16x32_bf16 v[114:117], v[134:137], v[174:177], v[114:117]
	v_mfma_f32_16x16x32_bf16 v[106:109], v[138:141], v[170:173], v[106:109]
	v_mfma_f32_16x16x32_bf16 v[106:109], v[142:145], v[174:177], v[106:109]
	v_mfma_f32_16x16x32_bf16 v[98:101], v[130:133], v[178:181], v[98:101]
	v_mfma_f32_16x16x32_bf16 v[98:101], v[134:137], v[182:185], v[98:101]
	v_mfma_f32_16x16x32_bf16 v[90:93], v[138:141], v[178:181], v[90:93]
	v_mfma_f32_16x16x32_bf16 v[90:93], v[142:145], v[182:185], v[90:93]
	v_mfma_f32_16x16x32_bf16 v[82:85], v[130:133], v[186:189], v[82:85]
	v_mfma_f32_16x16x32_bf16 v[82:85], v[134:137], v[190:193], v[82:85]
	v_mfma_f32_16x16x32_bf16 v[74:77], v[138:141], v[186:189], v[74:77]
	v_mfma_f32_16x16x32_bf16 v[74:77], v[142:145], v[190:193], v[74:77]
	s_setprio 0
	s_setprio 1
	v_mfma_f32_16x16x32_bf16 v[118:121], v[146:149], v[162:165], v[118:121]
	v_mfma_f32_16x16x32_bf16 v[118:121], v[150:153], v[166:169], v[118:121]
	v_mfma_f32_16x16x32_bf16 v[110:113], v[154:157], v[162:165], v[110:113]
	v_mfma_f32_16x16x32_bf16 v[110:113], v[158:161], v[166:169], v[110:113]
	v_mfma_f32_16x16x32_bf16 v[102:105], v[146:149], v[170:173], v[102:105]
	v_mfma_f32_16x16x32_bf16 v[102:105], v[150:153], v[174:177], v[102:105]
	v_mfma_f32_16x16x32_bf16 v[94:97], v[154:157], v[170:173], v[94:97]
	v_mfma_f32_16x16x32_bf16 v[94:97], v[158:161], v[174:177], v[94:97]
	s_setprio 3
	s_barrier
	v_mfma_f32_16x16x32_bf16 v[86:89], v[146:149], v[178:181], v[86:89]
	v_mfma_f32_16x16x32_bf16 v[86:89], v[150:153], v[182:185], v[86:89]
	v_mfma_f32_16x16x32_bf16 v[78:81], v[154:157], v[178:181], v[78:81]
	v_mfma_f32_16x16x32_bf16 v[78:81], v[158:161], v[182:185], v[78:81]
	v_mfma_f32_16x16x32_bf16 v[70:73], v[146:149], v[186:189], v[70:73]
	v_mfma_f32_16x16x32_bf16 v[70:73], v[150:153], v[190:193], v[70:73]
	v_mfma_f32_16x16x32_bf16 v[66:69], v[154:157], v[186:189], v[66:69]
	v_mfma_f32_16x16x32_bf16 v[66:69], v[158:161], v[190:193], v[66:69]
	s_setprio 0
	s_add_i32 s35, s35, s19
	v_lshl_add_u64 v[194:195], v[194:195], 0, s[22:23]
	s_mov_b32 m0, s35
	ds_read_b128 v[162:165], v245 offset:49152
	ds_read_b128 v[166:169], v245 offset:50176
	ds_read_b128 v[170:173], v245 offset:51200
	ds_read_b128 v[174:177], v245 offset:52224
	ds_read_b128 v[178:181], v245 offset:53248
	ds_read_b128 v[182:185], v245 offset:54272
	ds_read_b128 v[186:189], v245 offset:55296
	ds_read_b128 v[190:193], v245 offset:56320
	global_load_lds_dwordx4 v[194:195], off
	v_lshl_add_u64 v[194:195], v[196:197], 0, s[22:23]
	s_add_i32 m0, s35, 0x2000
	s_add_i32 s35, s84, s19
	global_load_lds_dwordx4 v[194:195], off
	v_lshl_add_u64 v[194:195], v[198:199], 0, s[22:23]
	s_mov_b32 m0, s35
	s_nop 0
	global_load_lds_dwordx4 v[194:195], off
	v_lshl_add_u64 v[194:195], v[200:201], 0, s[22:23]
	s_add_i32 m0, s35, 0x2000
	s_nop 0
	global_load_lds_dwordx4 v[194:195], off
	v_lshl_add_u64 v[194:195], v[202:203], 0, s[22:23]
	s_mov_b32 m0, s37
	s_nop 0
	global_load_lds_dwordx4 v[194:195], off
	v_lshl_add_u64 v[194:195], v[204:205], 0, s[22:23]
	s_mov_b32 m0, s40
	s_nop 0
	global_load_lds_dwordx4 v[194:195], off
	s_waitcnt vmcnt(8)
	s_waitcnt lgkmcnt(0)
	s_barrier
	s_setprio 1
	s_waitcnt lgkmcnt(0)
	v_mfma_f32_16x16x32_bf16 v[62:65], v[130:133], v[162:165], v[62:65]
	v_mfma_f32_16x16x32_bf16 v[62:65], v[134:137], v[166:169], v[62:65]
	v_mfma_f32_16x16x32_bf16 v[58:61], v[138:141], v[162:165], v[58:61]
	v_mfma_f32_16x16x32_bf16 v[58:61], v[142:145], v[166:169], v[58:61]
	v_mfma_f32_16x16x32_bf16 v[50:53], v[130:133], v[170:173], v[50:53]
	v_mfma_f32_16x16x32_bf16 v[50:53], v[134:137], v[174:177], v[50:53]
	v_mfma_f32_16x16x32_bf16 v[42:45], v[138:141], v[170:173], v[42:45]
	v_mfma_f32_16x16x32_bf16 v[42:45], v[142:145], v[174:177], v[42:45]
	v_mfma_f32_16x16x32_bf16 v[34:37], v[130:133], v[178:181], v[34:37]
	v_mfma_f32_16x16x32_bf16 v[34:37], v[134:137], v[182:185], v[34:37]
	v_mfma_f32_16x16x32_bf16 v[26:29], v[138:141], v[178:181], v[26:29]
	v_mfma_f32_16x16x32_bf16 v[26:29], v[142:145], v[182:185], v[26:29]
	v_mfma_f32_16x16x32_bf16 v[18:21], v[130:133], v[186:189], v[18:21]
	v_mfma_f32_16x16x32_bf16 v[18:21], v[134:137], v[190:193], v[18:21]
	v_mfma_f32_16x16x32_bf16 v[10:13], v[138:141], v[186:189], v[10:13]
	v_mfma_f32_16x16x32_bf16 v[10:13], v[142:145], v[190:193], v[10:13]
	s_setprio 0
	s_setprio 1
	v_mfma_f32_16x16x32_bf16 v[54:57], v[146:149], v[162:165], v[54:57]
	v_mfma_f32_16x16x32_bf16 v[54:57], v[150:153], v[166:169], v[54:57]
	v_mfma_f32_16x16x32_bf16 v[46:49], v[154:157], v[162:165], v[46:49]
	v_mfma_f32_16x16x32_bf16 v[46:49], v[158:161], v[166:169], v[46:49]
	v_mfma_f32_16x16x32_bf16 v[38:41], v[146:149], v[170:173], v[38:41]
	v_mfma_f32_16x16x32_bf16 v[38:41], v[150:153], v[174:177], v[38:41]
	v_mfma_f32_16x16x32_bf16 v[30:33], v[154:157], v[170:173], v[30:33]
	v_mfma_f32_16x16x32_bf16 v[30:33], v[158:161], v[174:177], v[30:33]
	s_setprio 3
	s_barrier
	v_mfma_f32_16x16x32_bf16 v[22:25], v[146:149], v[178:181], v[22:25]
	v_mfma_f32_16x16x32_bf16 v[22:25], v[150:153], v[182:185], v[22:25]
	v_mfma_f32_16x16x32_bf16 v[14:17], v[154:157], v[178:181], v[14:17]
	v_mfma_f32_16x16x32_bf16 v[14:17], v[158:161], v[182:185], v[14:17]
	v_mfma_f32_16x16x32_bf16 v[6:9], v[146:149], v[186:189], v[6:9]
	v_mfma_f32_16x16x32_bf16 v[6:9], v[150:153], v[190:193], v[6:9]
	v_mfma_f32_16x16x32_bf16 v[2:5], v[154:157], v[186:189], v[2:5]
	v_mfma_f32_16x16x32_bf16 v[2:5], v[158:161], v[190:193], v[2:5]
	s_setprio 0
	s_add_u32 s0, s0, 0x100
	s_addc_u32 s1, s1, 0
	s_add_u32 vcc_lo, vcc_lo, 0x100
	s_addc_u32 vcc_hi, vcc_hi, 0
	s_cmp_ge_u32 s34, s18
	s_mov_b32 s68, s34
	s_cbranch_scc0 .LBB0_707
	s_and_b64 vcc, exec, s[50:51]
	s_cbranch_vccz .LBB0_710
	s_barrier
